# P10 V^T epilogue: all 8 rstd loads up front, no vmcnt(0) between the 2-byte store groups (on top of rope epilogue prefetch + copy propagation)
# baseline (speedup 1.0000x reference)
.LBB0_1009:
	s_cmp_eq_u32 s7, 1
	s_mov_b64 s[60:61], -1
	s_cbranch_scc0 .LBB0_1011
	s_lshl_b32 s53, s6, 8
	s_add_i32 s53, s53, s90
	v_add_u32_e32 v140, s53, v182
	v_ashrrev_i32_e32 v141, 31, v140
	v_lshl_add_u64 v[142:143], v[140:141], 2, s[24:25]
	global_load_dword v230, v[142:143], off
	global_load_dword v231, v[142:143], off offset:64
	global_load_dword v232, v[142:143], off offset:128
	global_load_dword v233, v[142:143], off offset:192
	global_load_dword v234, v[142:143], off offset:512
	global_load_dword v235, v[142:143], off offset:576
	global_load_dword v236, v[142:143], off offset:640
	global_load_dword v237, v[142:143], off offset:704
	v_lshl_add_u32 v162, v181, 3, s91
	v_or_b32_e32 v150, 5, v162
	v_or_b32_e32 v168, 7, v162
	v_ashrrev_i32_e32 v190, 12, v140
	v_ashrrev_i32_e32 v151, 31, v150
	v_ashrrev_i32_e32 v169, 31, v168
	v_ashrrev_i32_e32 v191, 31, v190
	v_or_b32_e32 v144, 2, v162
	v_add_u32_e32 v184, 0x82, v162
	v_and_b32_e32 v132, 0xfff, v140
	v_lshlrev_b64 v[154:155], 13, v[150:151]
	v_lshlrev_b64 v[150:151], 13, v[168:169]
	v_lshlrev_b64 v[168:169], 21, v[190:191]
	v_ashrrev_i32_e32 v163, 31, v162
	v_or_b32_e32 v142, 1, v162
	v_ashrrev_i32_e32 v145, 31, v144
	v_ashrrev_i32_e32 v185, 31, v184
	v_lshlrev_b32_e32 v132, 1, v132
	v_lshl_add_u64 v[168:169], s[18:19], 0, v[168:169]
	v_or_b32_e32 v148, 4, v162
	v_add_u32_e32 v170, 0x80, v162
	v_lshlrev_b64 v[156:157], 13, v[162:163]
	v_ashrrev_i32_e32 v143, 31, v142
	v_lshlrev_b64 v[164:165], 13, v[144:145]
	v_lshlrev_b64 v[144:145], 13, v[184:185]
	v_lshl_add_u64 v[184:185], v[168:169], 0, v[132:133]
	v_or_b32_e32 v146, 3, v162
	v_add_u32_e32 v172, 0x81, v162
	v_ashrrev_i32_e32 v149, 31, v148
	v_ashrrev_i32_e32 v171, 31, v170
	v_lshlrev_b64 v[166:167], 13, v[142:143]
	v_lshl_add_u64 v[168:169], v[184:185], 0, v[156:157]
	v_add_u32_e32 v186, 0x83, v162
	v_ashrrev_i32_e32 v147, 31, v146
	v_ashrrev_i32_e32 v173, 31, v172
	v_lshlrev_b64 v[158:159], 13, v[148:149]
	v_lshlrev_b64 v[148:149], 13, v[170:171]
	v_lshl_add_u64 v[170:171], v[184:185], 0, v[166:167]
	v_ashrrev_i32_e32 v187, 31, v186
	v_lshlrev_b64 v[160:161], 13, v[146:147]
	v_lshlrev_b64 v[146:147], 13, v[172:173]
	v_lshl_add_u64 v[172:173], v[184:185], 0, v[164:165]
	v_or_b32_e32 v152, 6, v162
	v_lshlrev_b64 v[142:143], 13, v[186:187]
	v_lshl_add_u64 v[186:187], v[184:185], 0, v[160:161]
	v_ashrrev_i32_e32 v153, 31, v152
	v_lshl_add_u64 v[190:191], v[184:185], 0, v[158:159]
	v_lshlrev_b64 v[152:153], 13, v[152:153]
	v_lshl_add_u64 v[192:193], v[184:185], 0, v[154:155]
	v_lshl_add_u64 v[194:195], v[184:185], 0, v[152:153]
	v_lshl_add_u64 v[196:197], v[184:185], 0, v[150:151]
	v_add_u32_e32 v188, 0x84, v162
	v_lshl_add_u64 v[198:199], v[184:185], 0, v[148:149]
	v_lshl_add_u64 v[200:201], v[184:185], 0, v[146:147]
	v_lshl_add_u64 v[202:203], v[184:185], 0, v[144:145]
	v_lshl_add_u64 v[204:205], v[184:185], 0, v[142:143]
	s_waitcnt vmcnt(0)
	v_mul_f32_e32 v132, v120, v230
	v_cvt_pk_bf16_f32 v132, v132, v133
	v_mul_f32_e32 v163, v121, v230
	global_store_short v[168:169], v132, off
	v_cvt_pk_bf16_f32 v132, v163, v133
	v_mul_f32_e32 v183, v122, v230
	global_store_short v[170:171], v132, off
	v_cvt_pk_bf16_f32 v132, v183, v133
	v_mul_f32_e32 v189, v123, v230
	global_store_short v[172:173], v132, off
	v_cvt_pk_bf16_f32 v132, v189, v133
	v_mul_f32_e32 v206, v112, v230
	global_store_short v[186:187], v132, off
	v_cvt_pk_bf16_f32 v132, v206, v133
	v_mul_f32_e32 v207, v113, v230
	global_store_short v[190:191], v132, off
	v_cvt_pk_bf16_f32 v132, v207, v133
	v_mul_f32_e32 v208, v114, v230
	global_store_short v[192:193], v132, off
	v_cvt_pk_bf16_f32 v132, v208, v133
	v_mul_f32_e32 v209, v115, v230
	global_store_short v[194:195], v132, off
	v_cvt_pk_bf16_f32 v132, v209, v133
	v_mul_f32_e32 v210, v124, v230
	global_store_short v[196:197], v132, off
	v_cvt_pk_bf16_f32 v132, v210, v133
	v_mul_f32_e32 v211, v125, v230
	global_store_short v[198:199], v132, off
	v_cvt_pk_bf16_f32 v132, v211, v133
	v_ashrrev_i32_e32 v189, 31, v188
	v_mul_f32_e32 v212, v126, v230
	global_store_short v[200:201], v132, off
	v_cvt_pk_bf16_f32 v132, v212, v133
	v_lshlrev_b64 v[168:169], 13, v[188:189]
	v_mul_f32_e32 v213, v127, v230
	global_store_short v[202:203], v132, off
	v_cvt_pk_bf16_f32 v132, v213, v133
	v_lshl_add_u64 v[170:171], v[184:185], 0, v[168:169]
	v_mul_f32_e32 v214, v116, v230
	global_store_short v[204:205], v132, off
	v_cvt_pk_bf16_f32 v132, v214, v133
	global_store_short v[170:171], v132, off
	v_add_u32_e32 v170, 0x85, v162
	v_ashrrev_i32_e32 v171, 31, v170
	v_lshlrev_b64 v[170:171], 13, v[170:171]
	v_mul_f32_e32 v132, v117, v230
	v_lshl_add_u64 v[172:173], v[184:185], 0, v[170:171]
	v_cvt_pk_bf16_f32 v132, v132, v133
	global_store_short v[172:173], v132, off
	v_add_u32_e32 v172, 0x86, v162
	v_ashrrev_i32_e32 v173, 31, v172
	v_add_u32_e32 v162, 0x87, v162
	v_mul_f32_e32 v132, v118, v230
	v_lshlrev_b64 v[172:173], 13, v[172:173]
	v_ashrrev_i32_e32 v163, 31, v162
	v_cvt_pk_bf16_f32 v132, v132, v133
	v_lshl_add_u64 v[186:187], v[184:185], 0, v[172:173]
	v_lshlrev_b64 v[162:163], 13, v[162:163]
	global_store_short v[186:187], v132, off
	v_mul_f32_e32 v132, v119, v230
	v_lshl_add_u64 v[184:185], v[184:185], 0, v[162:163]
	v_cvt_pk_bf16_f32 v132, v132, v133
	global_store_short v[184:185], v132, off
	v_add_u32_e32 v184, 16, v140
	v_ashrrev_i32_e32 v185, 31, v184
	v_lshl_add_u64 v[186:187], v[184:185], 2, s[24:25]

	v_ashrrev_i32_e32 v186, 12, v184
	v_ashrrev_i32_e32 v187, 31, v186
	v_and_b32_e32 v132, 0xfff, v184
	v_lshlrev_b64 v[184:185], 21, v[186:187]
	v_lshlrev_b32_e32 v132, 1, v132
	v_lshl_add_u64 v[184:185], s[18:19], 0, v[184:185]
	v_lshl_add_u64 v[184:185], v[184:185], 0, v[132:133]
	v_lshl_add_u64 v[186:187], v[184:185], 0, v[156:157]
	v_lshl_add_u64 v[188:189], v[184:185], 0, v[166:167]
	v_lshl_add_u64 v[190:191], v[184:185], 0, v[164:165]
	v_lshl_add_u64 v[192:193], v[184:185], 0, v[160:161]
	v_lshl_add_u64 v[194:195], v[184:185], 0, v[158:159]
	v_lshl_add_u64 v[196:197], v[184:185], 0, v[154:155]
	v_lshl_add_u64 v[198:199], v[184:185], 0, v[152:153]
	v_lshl_add_u64 v[200:201], v[184:185], 0, v[150:151]
	v_lshl_add_u64 v[202:203], v[184:185], 0, v[148:149]
	v_lshl_add_u64 v[204:205], v[184:185], 0, v[146:147]
	v_lshl_add_u64 v[206:207], v[184:185], 0, v[144:145]
	v_lshl_add_u64 v[208:209], v[184:185], 0, v[142:143]
	v_lshl_add_u64 v[210:211], v[184:185], 0, v[168:169]
	v_lshl_add_u64 v[212:213], v[184:185], 0, v[170:171]
	v_lshl_add_u64 v[214:215], v[184:185], 0, v[172:173]
	v_lshl_add_u64 v[184:185], v[184:185], 0, v[162:163]

	v_mul_f32_e32 v132, v104, v231
	v_cvt_pk_bf16_f32 v132, v132, v133
	v_mul_f32_e32 v183, v105, v231
	global_store_short v[186:187], v132, off
	v_cvt_pk_bf16_f32 v132, v183, v133
	v_mul_f32_e32 v216, v106, v231
	global_store_short v[188:189], v132, off
	v_cvt_pk_bf16_f32 v132, v216, v133
	v_mul_f32_e32 v217, v107, v231
	global_store_short v[190:191], v132, off
	v_cvt_pk_bf16_f32 v132, v217, v133
	v_mul_f32_e32 v218, v96, v231
	global_store_short v[192:193], v132, off
	v_cvt_pk_bf16_f32 v132, v218, v133
	v_mul_f32_e32 v219, v97, v231
	global_store_short v[194:195], v132, off
	v_cvt_pk_bf16_f32 v132, v219, v133
	v_mul_f32_e32 v220, v98, v231
	global_store_short v[196:197], v132, off
	v_cvt_pk_bf16_f32 v132, v220, v133
	v_mul_f32_e32 v221, v99, v231
	global_store_short v[198:199], v132, off
	v_cvt_pk_bf16_f32 v132, v221, v133
	v_mul_f32_e32 v222, v108, v231
	global_store_short v[200:201], v132, off
	v_cvt_pk_bf16_f32 v132, v222, v133
	v_mul_f32_e32 v223, v109, v231
	global_store_short v[202:203], v132, off
	v_cvt_pk_bf16_f32 v132, v223, v133
	v_mul_f32_e32 v224, v110, v231
	global_store_short v[204:205], v132, off
	v_cvt_pk_bf16_f32 v132, v224, v133
	v_mul_f32_e32 v225, v111, v231
	global_store_short v[206:207], v132, off
	v_cvt_pk_bf16_f32 v132, v225, v133
	v_mul_f32_e32 v226, v100, v231
	global_store_short v[208:209], v132, off
	v_cvt_pk_bf16_f32 v132, v226, v133
	v_mul_f32_e32 v227, v101, v231
	global_store_short v[210:211], v132, off
	v_cvt_pk_bf16_f32 v132, v227, v133
	v_mul_f32_e32 v228, v102, v231
	global_store_short v[212:213], v132, off
	v_cvt_pk_bf16_f32 v132, v228, v133
	v_mul_f32_e32 v141, v103, v231
	global_store_short v[214:215], v132, off
	v_cvt_pk_bf16_f32 v132, v141, v133
	global_store_short v[184:185], v132, off
	v_add_u32_e32 v184, 32, v140
	v_ashrrev_i32_e32 v185, 31, v184
	v_lshl_add_u64 v[186:187], v[184:185], 2, s[24:25]

	v_ashrrev_i32_e32 v186, 12, v184
	v_ashrrev_i32_e32 v187, 31, v186
	v_and_b32_e32 v132, 0xfff, v184
	v_lshlrev_b64 v[184:185], 21, v[186:187]
	v_lshlrev_b32_e32 v132, 1, v132
	v_lshl_add_u64 v[184:185], s[18:19], 0, v[184:185]
	v_lshl_add_u64 v[184:185], v[184:185], 0, v[132:133]
	v_lshl_add_u64 v[186:187], v[184:185], 0, v[156:157]
	v_lshl_add_u64 v[188:189], v[184:185], 0, v[166:167]
	v_lshl_add_u64 v[190:191], v[184:185], 0, v[164:165]
	v_lshl_add_u64 v[192:193], v[184:185], 0, v[160:161]
	v_lshl_add_u64 v[194:195], v[184:185], 0, v[158:159]
	v_lshl_add_u64 v[196:197], v[184:185], 0, v[154:155]
	v_lshl_add_u64 v[198:199], v[184:185], 0, v[152:153]
	v_lshl_add_u64 v[200:201], v[184:185], 0, v[150:151]
	v_lshl_add_u64 v[202:203], v[184:185], 0, v[148:149]
	v_lshl_add_u64 v[204:205], v[184:185], 0, v[146:147]
	v_lshl_add_u64 v[206:207], v[184:185], 0, v[144:145]
	v_lshl_add_u64 v[208:209], v[184:185], 0, v[142:143]
	v_lshl_add_u64 v[210:211], v[184:185], 0, v[168:169]
	v_lshl_add_u64 v[212:213], v[184:185], 0, v[170:171]
	v_lshl_add_u64 v[214:215], v[184:185], 0, v[172:173]
	v_lshl_add_u64 v[184:185], v[184:185], 0, v[162:163]

	v_mul_f32_e32 v132, v88, v232
	v_cvt_pk_bf16_f32 v132, v132, v133
	v_mul_f32_e32 v183, v89, v232
	global_store_short v[186:187], v132, off
	v_cvt_pk_bf16_f32 v132, v183, v133
	v_mul_f32_e32 v216, v90, v232
	global_store_short v[188:189], v132, off
	v_cvt_pk_bf16_f32 v132, v216, v133
	v_mul_f32_e32 v217, v91, v232
	global_store_short v[190:191], v132, off
	v_cvt_pk_bf16_f32 v132, v217, v133
	v_mul_f32_e32 v218, v80, v232
	global_store_short v[192:193], v132, off
	v_cvt_pk_bf16_f32 v132, v218, v133
	v_mul_f32_e32 v219, v81, v232
	global_store_short v[194:195], v132, off
	v_cvt_pk_bf16_f32 v132, v219, v133
	v_mul_f32_e32 v220, v82, v232
	global_store_short v[196:197], v132, off
	v_cvt_pk_bf16_f32 v132, v220, v133
	v_mul_f32_e32 v221, v83, v232
	global_store_short v[198:199], v132, off
	v_cvt_pk_bf16_f32 v132, v221, v133
	v_mul_f32_e32 v222, v92, v232
	global_store_short v[200:201], v132, off
	v_cvt_pk_bf16_f32 v132, v222, v133
	v_mul_f32_e32 v223, v93, v232
	global_store_short v[202:203], v132, off
	v_cvt_pk_bf16_f32 v132, v223, v133
	v_mul_f32_e32 v224, v94, v232
	global_store_short v[204:205], v132, off
	v_cvt_pk_bf16_f32 v132, v224, v133
	v_mul_f32_e32 v225, v95, v232
	global_store_short v[206:207], v132, off
	v_cvt_pk_bf16_f32 v132, v225, v133
	v_mul_f32_e32 v226, v84, v232
	global_store_short v[208:209], v132, off
	v_cvt_pk_bf16_f32 v132, v226, v133
	v_mul_f32_e32 v227, v85, v232
	global_store_short v[210:211], v132, off
	v_cvt_pk_bf16_f32 v132, v227, v133
	v_mul_f32_e32 v228, v86, v232
	global_store_short v[212:213], v132, off
	v_cvt_pk_bf16_f32 v132, v228, v133
	v_mul_f32_e32 v141, v87, v232
	global_store_short v[214:215], v132, off
	v_cvt_pk_bf16_f32 v132, v141, v133
	global_store_short v[184:185], v132, off
	v_add_u32_e32 v184, 48, v140
	v_ashrrev_i32_e32 v185, 31, v184
	v_lshl_add_u64 v[186:187], v[184:185], 2, s[24:25]

	v_ashrrev_i32_e32 v186, 12, v184
	v_ashrrev_i32_e32 v187, 31, v186
	v_and_b32_e32 v132, 0xfff, v184
	v_lshlrev_b64 v[184:185], 21, v[186:187]
	v_lshlrev_b32_e32 v132, 1, v132
	v_lshl_add_u64 v[184:185], s[18:19], 0, v[184:185]
	v_lshl_add_u64 v[184:185], v[184:185], 0, v[132:133]
	v_lshl_add_u64 v[186:187], v[184:185], 0, v[156:157]
	v_lshl_add_u64 v[188:189], v[184:185], 0, v[166:167]
	v_lshl_add_u64 v[190:191], v[184:185], 0, v[164:165]
	v_lshl_add_u64 v[192:193], v[184:185], 0, v[160:161]
	v_lshl_add_u64 v[194:195], v[184:185], 0, v[158:159]
	v_lshl_add_u64 v[196:197], v[184:185], 0, v[154:155]
	v_lshl_add_u64 v[198:199], v[184:185], 0, v[152:153]
	v_lshl_add_u64 v[200:201], v[184:185], 0, v[150:151]
	v_lshl_add_u64 v[202:203], v[184:185], 0, v[148:149]
	v_lshl_add_u64 v[204:205], v[184:185], 0, v[146:147]
	v_lshl_add_u64 v[206:207], v[184:185], 0, v[144:145]
	v_lshl_add_u64 v[208:209], v[184:185], 0, v[142:143]
	v_lshl_add_u64 v[210:211], v[184:185], 0, v[168:169]
	v_lshl_add_u64 v[212:213], v[184:185], 0, v[170:171]
	v_lshl_add_u64 v[214:215], v[184:185], 0, v[172:173]
	v_lshl_add_u64 v[184:185], v[184:185], 0, v[162:163]

	v_mul_f32_e32 v132, v72, v233
	v_cvt_pk_bf16_f32 v132, v132, v133
	v_mul_f32_e32 v183, v73, v233
	global_store_short v[186:187], v132, off
	v_cvt_pk_bf16_f32 v132, v183, v133
	v_mul_f32_e32 v216, v74, v233
	global_store_short v[188:189], v132, off
	v_cvt_pk_bf16_f32 v132, v216, v133
	v_mul_f32_e32 v217, v75, v233
	global_store_short v[190:191], v132, off
	v_cvt_pk_bf16_f32 v132, v217, v133
	v_mul_f32_e32 v218, v64, v233
	global_store_short v[192:193], v132, off
	v_cvt_pk_bf16_f32 v132, v218, v133
	v_mul_f32_e32 v219, v65, v233
	global_store_short v[194:195], v132, off
	v_cvt_pk_bf16_f32 v132, v219, v133
	v_mul_f32_e32 v220, v66, v233
	global_store_short v[196:197], v132, off
	v_cvt_pk_bf16_f32 v132, v220, v133
	v_mul_f32_e32 v221, v67, v233
	global_store_short v[198:199], v132, off
	v_cvt_pk_bf16_f32 v132, v221, v133
	v_mul_f32_e32 v222, v76, v233
	global_store_short v[200:201], v132, off
	v_cvt_pk_bf16_f32 v132, v222, v133
	v_mul_f32_e32 v223, v77, v233
	global_store_short v[202:203], v132, off
	v_cvt_pk_bf16_f32 v132, v223, v133
	v_mul_f32_e32 v224, v78, v233
	global_store_short v[204:205], v132, off
	v_cvt_pk_bf16_f32 v132, v224, v133
	v_mul_f32_e32 v225, v79, v233
	global_store_short v[206:207], v132, off
	v_cvt_pk_bf16_f32 v132, v225, v133
	v_mul_f32_e32 v226, v68, v233
	global_store_short v[208:209], v132, off
	v_cvt_pk_bf16_f32 v132, v226, v133
	v_mul_f32_e32 v227, v69, v233
	global_store_short v[210:211], v132, off
	v_cvt_pk_bf16_f32 v132, v227, v133
	v_mul_f32_e32 v228, v70, v233
	global_store_short v[212:213], v132, off
	v_cvt_pk_bf16_f32 v132, v228, v133
	v_mul_f32_e32 v141, v71, v233
	global_store_short v[214:215], v132, off
	v_cvt_pk_bf16_f32 v132, v141, v133
	global_store_short v[184:185], v132, off
	v_add_u32_e32 v184, 0x80, v140
	v_ashrrev_i32_e32 v185, 31, v184
	v_lshl_add_u64 v[186:187], v[184:185], 2, s[24:25]

	v_ashrrev_i32_e32 v186, 12, v184
	v_ashrrev_i32_e32 v187, 31, v186
	v_and_b32_e32 v132, 0xfff, v184
	v_lshlrev_b64 v[184:185], 21, v[186:187]
	v_lshlrev_b32_e32 v132, 1, v132
	v_lshl_add_u64 v[184:185], s[18:19], 0, v[184:185]
	v_lshl_add_u64 v[184:185], v[184:185], 0, v[132:133]
	v_lshl_add_u64 v[186:187], v[184:185], 0, v[156:157]
	v_lshl_add_u64 v[188:189], v[184:185], 0, v[166:167]
	v_lshl_add_u64 v[190:191], v[184:185], 0, v[164:165]
	v_lshl_add_u64 v[192:193], v[184:185], 0, v[160:161]
	v_lshl_add_u64 v[194:195], v[184:185], 0, v[158:159]
	v_lshl_add_u64 v[196:197], v[184:185], 0, v[154:155]
	v_lshl_add_u64 v[198:199], v[184:185], 0, v[152:153]
	v_lshl_add_u64 v[200:201], v[184:185], 0, v[150:151]
	v_lshl_add_u64 v[202:203], v[184:185], 0, v[148:149]
	v_lshl_add_u64 v[204:205], v[184:185], 0, v[146:147]
	v_lshl_add_u64 v[206:207], v[184:185], 0, v[144:145]
	v_lshl_add_u64 v[208:209], v[184:185], 0, v[142:143]
	v_lshl_add_u64 v[210:211], v[184:185], 0, v[168:169]
	v_lshl_add_u64 v[212:213], v[184:185], 0, v[170:171]
	v_lshl_add_u64 v[214:215], v[184:185], 0, v[172:173]
	v_lshl_add_u64 v[184:185], v[184:185], 0, v[162:163]

	v_mul_f32_e32 v132, v56, v234
	v_cvt_pk_bf16_f32 v132, v132, v133
	v_mul_f32_e32 v183, v57, v234
	global_store_short v[186:187], v132, off
	v_cvt_pk_bf16_f32 v132, v183, v133
	v_mul_f32_e32 v216, v58, v234
	global_store_short v[188:189], v132, off
	v_cvt_pk_bf16_f32 v132, v216, v133
	v_mul_f32_e32 v217, v59, v234
	global_store_short v[190:191], v132, off
	v_cvt_pk_bf16_f32 v132, v217, v133
	v_mul_f32_e32 v218, v48, v234
	global_store_short v[192:193], v132, off
	v_cvt_pk_bf16_f32 v132, v218, v133
	v_mul_f32_e32 v219, v49, v234
	global_store_short v[194:195], v132, off
	v_cvt_pk_bf16_f32 v132, v219, v133
	v_mul_f32_e32 v220, v50, v234
	global_store_short v[196:197], v132, off
	v_cvt_pk_bf16_f32 v132, v220, v133
	v_mul_f32_e32 v221, v51, v234
	global_store_short v[198:199], v132, off
	v_cvt_pk_bf16_f32 v132, v221, v133
	v_mul_f32_e32 v222, v60, v234
	global_store_short v[200:201], v132, off
	v_cvt_pk_bf16_f32 v132, v222, v133
	v_mul_f32_e32 v223, v61, v234
	global_store_short v[202:203], v132, off
	v_cvt_pk_bf16_f32 v132, v223, v133
	v_mul_f32_e32 v224, v62, v234
	global_store_short v[204:205], v132, off
	v_cvt_pk_bf16_f32 v132, v224, v133
	v_mul_f32_e32 v225, v63, v234
	global_store_short v[206:207], v132, off
	v_cvt_pk_bf16_f32 v132, v225, v133
	v_mul_f32_e32 v226, v52, v234
	global_store_short v[208:209], v132, off
	v_cvt_pk_bf16_f32 v132, v226, v133
	v_mul_f32_e32 v227, v53, v234
	global_store_short v[210:211], v132, off
	v_cvt_pk_bf16_f32 v132, v227, v133
	v_mul_f32_e32 v228, v54, v234
	global_store_short v[212:213], v132, off
	v_cvt_pk_bf16_f32 v132, v228, v133
	v_mul_f32_e32 v141, v55, v234
	global_store_short v[214:215], v132, off
	v_cvt_pk_bf16_f32 v132, v141, v133
	global_store_short v[184:185], v132, off
	v_add_u32_e32 v184, 0x90, v140
	v_ashrrev_i32_e32 v185, 31, v184
	v_lshl_add_u64 v[186:187], v[184:185], 2, s[24:25]

	v_ashrrev_i32_e32 v186, 12, v184
	v_ashrrev_i32_e32 v187, 31, v186
	v_and_b32_e32 v132, 0xfff, v184
	v_lshlrev_b64 v[184:185], 21, v[186:187]
	v_lshlrev_b32_e32 v132, 1, v132
	v_lshl_add_u64 v[184:185], s[18:19], 0, v[184:185]
	v_lshl_add_u64 v[184:185], v[184:185], 0, v[132:133]
	v_lshl_add_u64 v[186:187], v[184:185], 0, v[156:157]
	v_lshl_add_u64 v[188:189], v[184:185], 0, v[166:167]
	v_lshl_add_u64 v[190:191], v[184:185], 0, v[164:165]
	v_lshl_add_u64 v[192:193], v[184:185], 0, v[160:161]
	v_lshl_add_u64 v[194:195], v[184:185], 0, v[158:159]
	v_lshl_add_u64 v[196:197], v[184:185], 0, v[154:155]
	v_lshl_add_u64 v[198:199], v[184:185], 0, v[152:153]
	v_lshl_add_u64 v[200:201], v[184:185], 0, v[150:151]
	v_lshl_add_u64 v[202:203], v[184:185], 0, v[148:149]
	v_lshl_add_u64 v[204:205], v[184:185], 0, v[146:147]
	v_lshl_add_u64 v[206:207], v[184:185], 0, v[144:145]
	v_lshl_add_u64 v[208:209], v[184:185], 0, v[142:143]
	v_lshl_add_u64 v[210:211], v[184:185], 0, v[168:169]
	v_lshl_add_u64 v[212:213], v[184:185], 0, v[170:171]
	v_lshl_add_u64 v[214:215], v[184:185], 0, v[172:173]
	v_lshl_add_u64 v[184:185], v[184:185], 0, v[162:163]

	v_mul_f32_e32 v132, v40, v235
	v_cvt_pk_bf16_f32 v132, v132, v133
	v_mul_f32_e32 v183, v41, v235
	global_store_short v[186:187], v132, off
	v_cvt_pk_bf16_f32 v132, v183, v133
	v_mul_f32_e32 v216, v42, v235
	global_store_short v[188:189], v132, off
	v_cvt_pk_bf16_f32 v132, v216, v133
	v_mul_f32_e32 v217, v43, v235
	global_store_short v[190:191], v132, off
	v_cvt_pk_bf16_f32 v132, v217, v133
	v_mul_f32_e32 v218, v32, v235
	global_store_short v[192:193], v132, off
	v_cvt_pk_bf16_f32 v132, v218, v133
	v_mul_f32_e32 v219, v33, v235
	global_store_short v[194:195], v132, off
	v_cvt_pk_bf16_f32 v132, v219, v133
	v_mul_f32_e32 v220, v34, v235
	global_store_short v[196:197], v132, off
	v_cvt_pk_bf16_f32 v132, v220, v133
	v_mul_f32_e32 v221, v35, v235
	global_store_short v[198:199], v132, off
	v_cvt_pk_bf16_f32 v132, v221, v133
	v_mul_f32_e32 v222, v44, v235
	global_store_short v[200:201], v132, off
	v_cvt_pk_bf16_f32 v132, v222, v133
	v_mul_f32_e32 v223, v45, v235
	global_store_short v[202:203], v132, off
	v_cvt_pk_bf16_f32 v132, v223, v133
	v_mul_f32_e32 v224, v46, v235
	global_store_short v[204:205], v132, off
	v_cvt_pk_bf16_f32 v132, v224, v133
	v_mul_f32_e32 v225, v47, v235
	global_store_short v[206:207], v132, off
	v_cvt_pk_bf16_f32 v132, v225, v133
	v_mul_f32_e32 v226, v36, v235
	global_store_short v[208:209], v132, off
	v_cvt_pk_bf16_f32 v132, v226, v133
	v_mul_f32_e32 v227, v37, v235
	global_store_short v[210:211], v132, off
	v_cvt_pk_bf16_f32 v132, v227, v133
	v_mul_f32_e32 v228, v38, v235
	global_store_short v[212:213], v132, off
	v_cvt_pk_bf16_f32 v132, v228, v133
	v_mul_f32_e32 v141, v39, v235
	global_store_short v[214:215], v132, off
	v_cvt_pk_bf16_f32 v132, v141, v133
	global_store_short v[184:185], v132, off
	v_add_u32_e32 v184, 0xa0, v140
	v_ashrrev_i32_e32 v185, 31, v184
	v_lshl_add_u64 v[186:187], v[184:185], 2, s[24:25]

	v_ashrrev_i32_e32 v186, 12, v184
	v_ashrrev_i32_e32 v187, 31, v186
	v_and_b32_e32 v132, 0xfff, v184
	v_lshlrev_b64 v[184:185], 21, v[186:187]
	v_lshlrev_b32_e32 v132, 1, v132
	v_lshl_add_u64 v[184:185], s[18:19], 0, v[184:185]
	v_lshl_add_u64 v[184:185], v[184:185], 0, v[132:133]
	v_lshl_add_u64 v[186:187], v[184:185], 0, v[156:157]
	v_lshl_add_u64 v[188:189], v[184:185], 0, v[166:167]
	v_lshl_add_u64 v[190:191], v[184:185], 0, v[164:165]
	v_lshl_add_u64 v[192:193], v[184:185], 0, v[160:161]
	v_lshl_add_u64 v[194:195], v[184:185], 0, v[158:159]
	v_lshl_add_u64 v[196:197], v[184:185], 0, v[154:155]
	v_lshl_add_u64 v[198:199], v[184:185], 0, v[152:153]
	v_lshl_add_u64 v[200:201], v[184:185], 0, v[150:151]
	v_lshl_add_u64 v[202:203], v[184:185], 0, v[148:149]
	v_lshl_add_u64 v[204:205], v[184:185], 0, v[146:147]
	v_lshl_add_u64 v[206:207], v[184:185], 0, v[144:145]
	v_lshl_add_u64 v[208:209], v[184:185], 0, v[142:143]
	v_lshl_add_u64 v[210:211], v[184:185], 0, v[168:169]
	v_lshl_add_u64 v[212:213], v[184:185], 0, v[170:171]
	v_lshl_add_u64 v[214:215], v[184:185], 0, v[172:173]
	v_lshl_add_u64 v[184:185], v[184:185], 0, v[162:163]

	v_mul_f32_e32 v132, v24, v236
	v_cvt_pk_bf16_f32 v132, v132, v133
	v_mul_f32_e32 v183, v25, v236
	global_store_short v[186:187], v132, off
	v_cvt_pk_bf16_f32 v132, v183, v133
	v_mul_f32_e32 v216, v26, v236
	global_store_short v[188:189], v132, off
	v_cvt_pk_bf16_f32 v132, v216, v133
	v_mul_f32_e32 v217, v27, v236
	global_store_short v[190:191], v132, off
	v_cvt_pk_bf16_f32 v132, v217, v133
	v_mul_f32_e32 v218, v16, v236
	global_store_short v[192:193], v132, off
	v_cvt_pk_bf16_f32 v132, v218, v133
	v_mul_f32_e32 v219, v17, v236
	global_store_short v[194:195], v132, off
	v_cvt_pk_bf16_f32 v132, v219, v133
	v_mul_f32_e32 v220, v18, v236
	global_store_short v[196:197], v132, off
	v_cvt_pk_bf16_f32 v132, v220, v133
	v_mul_f32_e32 v221, v19, v236
	global_store_short v[198:199], v132, off
	v_cvt_pk_bf16_f32 v132, v221, v133
	v_mul_f32_e32 v222, v28, v236
	global_store_short v[200:201], v132, off
	v_cvt_pk_bf16_f32 v132, v222, v133
	v_mul_f32_e32 v223, v29, v236
	global_store_short v[202:203], v132, off
	v_cvt_pk_bf16_f32 v132, v223, v133
	v_mul_f32_e32 v224, v30, v236
	global_store_short v[204:205], v132, off
	v_cvt_pk_bf16_f32 v132, v224, v133
	v_mul_f32_e32 v225, v31, v236
	global_store_short v[206:207], v132, off
	v_cvt_pk_bf16_f32 v132, v225, v133
	v_mul_f32_e32 v226, v20, v236
	global_store_short v[208:209], v132, off
	v_cvt_pk_bf16_f32 v132, v226, v133
	v_mul_f32_e32 v227, v21, v236
	global_store_short v[210:211], v132, off
	v_cvt_pk_bf16_f32 v132, v227, v133
	v_mul_f32_e32 v228, v22, v236
	global_store_short v[212:213], v132, off
	v_cvt_pk_bf16_f32 v132, v228, v133
	v_mul_f32_e32 v141, v23, v236
	global_store_short v[214:215], v132, off
	v_cvt_pk_bf16_f32 v132, v141, v133
	global_store_short v[184:185], v132, off
	v_add_u32_e32 v140, 0xb0, v140
	v_ashrrev_i32_e32 v141, 31, v140
	v_lshl_add_u64 v[184:185], v[140:141], 2, s[24:25]

	v_ashrrev_i32_e32 v184, 12, v140
	v_ashrrev_i32_e32 v185, 31, v184
	v_and_b32_e32 v132, 0xfff, v140
	v_lshlrev_b64 v[140:141], 21, v[184:185]
	v_lshlrev_b32_e32 v132, 1, v132
	v_lshl_add_u64 v[140:141], s[18:19], 0, v[140:141]
	v_lshl_add_u64 v[140:141], v[140:141], 0, v[132:133]
	v_lshl_add_u64 v[156:157], v[140:141], 0, v[156:157]
	v_lshl_add_u64 v[166:167], v[140:141], 0, v[166:167]
	v_lshl_add_u64 v[164:165], v[140:141], 0, v[164:165]
	v_lshl_add_u64 v[160:161], v[140:141], 0, v[160:161]
	v_lshl_add_u64 v[158:159], v[140:141], 0, v[158:159]
	v_lshl_add_u64 v[154:155], v[140:141], 0, v[154:155]
	v_lshl_add_u64 v[152:153], v[140:141], 0, v[152:153]
	v_lshl_add_u64 v[150:151], v[140:141], 0, v[150:151]
	v_lshl_add_u64 v[148:149], v[140:141], 0, v[148:149]
	v_lshl_add_u64 v[146:147], v[140:141], 0, v[146:147]
	v_lshl_add_u64 v[144:145], v[140:141], 0, v[144:145]
	v_lshl_add_u64 v[142:143], v[140:141], 0, v[142:143]
	v_lshl_add_u64 v[168:169], v[140:141], 0, v[168:169]
	v_lshl_add_u64 v[170:171], v[140:141], 0, v[170:171]
	v_lshl_add_u64 v[172:173], v[140:141], 0, v[172:173]
	v_lshl_add_u64 v[140:141], v[140:141], 0, v[162:163]

	v_mul_f32_e32 v132, v8, v237
	v_cvt_pk_bf16_f32 v132, v132, v133
	v_mul_f32_e32 v184, v9, v237
	global_store_short v[156:157], v132, off
	v_cvt_pk_bf16_f32 v132, v184, v133
	v_mul_f32_e32 v185, v10, v237
	global_store_short v[166:167], v132, off
	v_cvt_pk_bf16_f32 v132, v185, v133
	v_mul_f32_e32 v186, v11, v237
	global_store_short v[164:165], v132, off
	v_cvt_pk_bf16_f32 v132, v186, v133
	v_mul_f32_e32 v187, v0, v237
	global_store_short v[160:161], v132, off
	v_cvt_pk_bf16_f32 v132, v187, v133
	v_mul_f32_e32 v188, v1, v237
	global_store_short v[158:159], v132, off
	v_cvt_pk_bf16_f32 v132, v188, v133
	v_mul_f32_e32 v189, v2, v237
	global_store_short v[154:155], v132, off
	v_cvt_pk_bf16_f32 v132, v189, v133
	v_mul_f32_e32 v190, v3, v237
	global_store_short v[152:153], v132, off
	v_cvt_pk_bf16_f32 v132, v190, v133
	v_mul_f32_e32 v191, v12, v237
	global_store_short v[150:151], v132, off
	v_cvt_pk_bf16_f32 v132, v191, v133
	v_mul_f32_e32 v192, v13, v237
	global_store_short v[148:149], v132, off
	v_cvt_pk_bf16_f32 v132, v192, v133
	v_mul_f32_e32 v193, v14, v237
	global_store_short v[146:147], v132, off
	v_cvt_pk_bf16_f32 v132, v193, v133
	v_mul_f32_e32 v194, v15, v237
	global_store_short v[144:145], v132, off
	v_cvt_pk_bf16_f32 v132, v194, v133
	v_mul_f32_e32 v195, v4, v237
	global_store_short v[142:143], v132, off
	v_cvt_pk_bf16_f32 v132, v195, v133
	v_mul_f32_e32 v196, v5, v237
	global_store_short v[168:169], v132, off
	v_cvt_pk_bf16_f32 v132, v196, v133
	v_mul_f32_e32 v197, v6, v237
	global_store_short v[170:171], v132, off
	v_cvt_pk_bf16_f32 v132, v197, v133
	v_mul_f32_e32 v183, v7, v237
	global_store_short v[172:173], v132, off
	v_cvt_pk_bf16_f32 v132, v183, v133
	global_store_short v[140:141], v132, off
	s_mov_b64 s[60:61], 0
